# attnA: second half of each tile's row-sum adds moved into the next step's first-half MFMA gaps
# speedup vs baseline: 1.0033x; 1.0032x over previous
; #define FA_SB() __builtin_amdgcn_sched_barrier(0)
; __device__ __forceinline__ float fadd_s(float a, float b) { float r; asm("v_add_f32_e32 %0, %1, %2" : "=v"(r) : "v"(a), "v"(b)); return r; }
; __device__ __forceinline__ void attn_unit_a(FLAS unsigned char* lds, const Unit u) {
;     ...
;         u32x4 vr[3];
; #pragma unroll
;         for (int m = 0; m < 3; ++m) vr[m] = FA_VFRAG(m);
;         const float off = cbC - mrun;
;         FA_SB();
;         float ra, rb, rm;
;         FA_PVM(0); pC0[0] = fadd_s(pC0[0], off); pC1[0] = fadd_s(pC1[0], off); pC0[1] = fadd_s(pC0[1], off); pC1[1] = fadd_s(pC1[1], off); pC0[2] = fadd_s(pC0[2], off); pC1[2] = fadd_s(pC1[2], off); FA_SB();
;         FA_PVM(1); ra = __builtin_fmaxf(__builtin_fmaxf(pC0[0], pC0[1]), pC0[2]); rb = __builtin_fmaxf(__builtin_fmaxf(pC1[0], pC1[1]), pC1[2]); pC0[3] = fadd_s(pC0[3], off); pC1[3] = fadd_s(pC1[3], off); pC0[4] = fadd_s(pC0[4], off); pC1[4] = fadd_s(pC1[4], off); FA_SB();
;         FA_PVM(2); ra = __builtin_fmaxf(__builtin_fmaxf(ra, pC0[3]), pC0[4]); rb = __builtin_fmaxf(__builtin_fmaxf(rb, pC1[3]), pC1[4]); pC0[5] = fadd_s(pC0[5], off); pC1[5] = fadd_s(pC1[5], off); pC0[6] = fadd_s(pC0[6], off); pC1[6] = fadd_s(pC1[6], off); FA_SB();
;         FA_PVM(3); ra = __builtin_fmaxf(__builtin_fmaxf(ra, pC0[5]), pC0[6]); rb = __builtin_fmaxf(__builtin_fmaxf(rb, pC1[5]), pC1[6]); pC0[7] = fadd_s(pC0[7], off); pC1[7] = fadd_s(pC1[7], off); pC0[8] = fadd_s(pC0[8], off); pC1[8] = fadd_s(pC1[8], off); FA_SB();
;         FA_PVM(4); ra = __builtin_fmaxf(__builtin_fmaxf(ra, pC0[7]), pC0[8]); rb = __builtin_fmaxf(__builtin_fmaxf(rb, pC1[7]), pC1[8]); pC0[9] = fadd_s(pC0[9], off); pC1[9] = fadd_s(pC1[9], off); pC0[10] = fadd_s(pC0[10], off); pC1[10] = fadd_s(pC1[10], off); FA_SB();
;         FA_PVM(5); ra = __builtin_fmaxf(__builtin_fmaxf(ra, pC0[9]), pC0[10]); rb = __builtin_fmaxf(__builtin_fmaxf(rb, pC1[9]), pC1[10]); pC0[11] = fadd_s(pC0[11], off); pC1[11] = fadd_s(pC1[11], off); pC0[12] = fadd_s(pC0[12], off); pC1[12] = fadd_s(pC1[12], off); FA_SB();
;         FA_PVM(6); ra = __builtin_fmaxf(__builtin_fmaxf(ra, pC0[11]), pC0[12]); rb = __builtin_fmaxf(__builtin_fmaxf(rb, pC1[11]), pC1[12]); pC0[13] = fadd_s(pC0[13], off); pC1[13] = fadd_s(pC1[13], off); pC0[14] = fadd_s(pC0[14], off); pC1[14] = fadd_s(pC1[14], off); FA_SB();
.LBB0_437:
	s_add_i32 s12, s19, -1
	s_xor_b64 s[20:21], s[24:25], -1
	s_and_b32 s18, s12, 3
	s_mulk_i32 s18, 0x4800
	s_cmp_lg_u32 s49, 0
	s_cselect_b32 s12, s18, 0
	v_add_u32_e32 v200, s12, v251
	ds_read_b128 v[128:131], v200 offset:16384
	ds_read_b128 v[132:135], v200 offset:20992
	ds_read_b128 v[136:139], v200 offset:25600
	s_waitcnt lgkmcnt(2)
	v_mfma_f32_32x32x16_bf16 v[48:63], v[128:131], v[204:207], v[48:63]
	ds_read_b128 v[128:131], v200 offset:30208
	v_max3_f32 v140, v96, v97, v98
	v_max3_f32 v141, v112, v113, v114
	v_cvt_pk_bf16_f32 v196, v72, v73
	v_cvt_pk_bf16_f32 v197, v74, v75
	v_add_f32_e32 v212, v80, v212
	v_add_f32_e32 v212, v81, v212
	s_waitcnt lgkmcnt(2)
	v_mfma_f32_32x32x16_bf16 v[32:47], v[132:135], v[204:207], v[32:47]
	ds_read_b128 v[132:135], v200 offset:16416
	v_max3_f32 v140, v140, v99, v100
	v_max3_f32 v141, v141, v115, v116
	v_cvt_pk_bf16_f32 v198, v76, v77
	v_cvt_pk_bf16_f32 v199, v78, v79
	v_add_f32_e32 v212, v82, v212
	v_add_f32_e32 v212, v83, v212
	s_waitcnt lgkmcnt(2)
	v_mfma_f32_32x32x16_bf16 v[16:31], v[136:139], v[204:207], v[16:31]
	ds_read_b128 v[136:139], v200 offset:21024
	v_max3_f32 v140, v140, v101, v102
	v_max3_f32 v141, v141, v117, v118
	v_cvt_pk_bf16_f32 v192, v80, v81
	v_cvt_pk_bf16_f32 v193, v82, v83
	v_add_f32_e32 v212, v84, v212
	v_add_f32_e32 v212, v85, v212
	s_waitcnt lgkmcnt(2)
	v_mfma_f32_32x32x16_bf16 v[0:15], v[128:131], v[204:207], v[0:15]
	ds_read_b128 v[128:131], v200 offset:25632
	v_max3_f32 v140, v140, v103, v104
	v_max3_f32 v141, v141, v119, v120
	v_cvt_pk_bf16_f32 v194, v84, v85
	v_cvt_pk_bf16_f32 v195, v86, v87
	v_add_f32_e32 v212, v86, v212
	v_add_f32_e32 v212, v87, v212
	s_waitcnt lgkmcnt(2)
	v_mfma_f32_32x32x16_bf16 v[48:63], v[132:135], v[196:199], v[48:63]
	ds_read_b128 v[132:135], v200 offset:30240
	v_max3_f32 v140, v140, v105, v106
	v_max3_f32 v141, v141, v121, v122
	v_cvt_pk_bf16_f32 v188, v88, v89
	v_cvt_pk_bf16_f32 v189, v90, v91
	v_add_f32_e32 v212, v88, v212
	v_add_f32_e32 v212, v89, v212
	s_waitcnt lgkmcnt(2)
	v_mfma_f32_32x32x16_bf16 v[32:47], v[136:139], v[196:199], v[32:47]
	ds_read_b128 v[136:139], v200 offset:16448
	v_max3_f32 v140, v140, v107, v108
	v_max3_f32 v141, v141, v123, v124
	v_cvt_pk_bf16_f32 v190, v92, v93
	v_cvt_pk_bf16_f32 v191, v94, v95
	v_add_f32_e32 v212, v90, v212
	v_add_f32_e32 v212, v91, v212
	s_waitcnt lgkmcnt(2)
	v_mfma_f32_32x32x16_bf16 v[16:31], v[128:131], v[196:199], v[16:31]
	ds_read_b128 v[128:131], v200 offset:21056
	v_max3_f32 v140, v140, v109, v110
	v_max3_f32 v141, v141, v125, v126
	v_add_f32_e32 v212, v92, v212
	v_add_f32_e32 v212, v93, v212
	s_waitcnt lgkmcnt(2)
	v_mfma_f32_32x32x16_bf16 v[0:15], v[132:135], v[196:199], v[0:15]
	ds_read_b128 v[132:135], v200 offset:25664
	v_max3_f32 v140, v140, v141, v111
	v_max_f32_e32 v140, v140, v127
	v_add_f32_e32 v212, v94, v212
	v_add_f32_e32 v212, v95, v212
	v_mov_b32_e32 v141, v140
	s_nop 1
	v_permlane32_swap_b32 v140, v141
	s_nop 1
	s_nop 0
	v_max_f32_e32 v140, v140, v141
	s_andn2_b64 vcc, exec, s[20:21]
	s_cbranch_vccnz .LBB0_440
	v_cmp_lt_f32_e32 vcc, s39, v140
	s_cmp_lg_u64 vcc, 0
	s_mov_b32 s12, 0
	s_cselect_b64 s[14:15], -1, 0
	v_mov_b32_e32 v141, v211
	s_andn2_b64 vcc, exec, s[14:15]
	s_cbranch_vccz .LBB0_441

; #define FA_SB() __builtin_amdgcn_sched_barrier(0)
; #define FA_EXP2(J, PX, R) do { const float e0_ = __builtin_amdgcn_exp2f(PX[R]), e1_ = __builtin_amdgcn_exp2f(PX[(R) + 1]); ps += e0_; ps += e1_; PWN[(J) >> 2][(J) & 3] = cvtpk(e0_, e1_); } while (0)
; __device__ __forceinline__ void attn_unit_a(FLAS unsigned char* lds, const Unit u) {
;     ...
;         float cbN; bool ziN; const int inx = (i + 1 < NT) ? i + 1 : NT - 1;
;         FA_BIAS(inx, pN0, pN1, cbN, ziN);
;         FA_SB();
;         if (ziN) { pN0 = __builtin_amdgcn_mfma_f32_32x32x16_bf16(kf[0], qr[0], z16, 0, 0, 0); FA_EXP2(8, pC1, 0); FA_SB(); pN1 = __builtin_amdgcn_mfma_f32_32x32x16_bf16(kf[1], qr[0], z16, 0, 0, 0); }
;         else { pN0 = __builtin_amdgcn_mfma_f32_32x32x16_bf16(kf[0], qr[0], pN0, 0, 0, 0); FA_EXP2(8, pC1, 0); FA_SB(); pN1 = __builtin_amdgcn_mfma_f32_32x32x16_bf16(kf[1], qr[0], pN1, 0, 0, 0); }
;         kf[0] = FA_KF(2, 0); kf[1] = FA_KF(2, 1); FA_EXP2(9, pC1, 2); FA_SB();
;         pN0 = __builtin_amdgcn_mfma_f32_32x32x16_bf16(kf[2], qr[1], pN0, 0, 0, 0); FA_EXP2(10, pC1, 4); FA_SB();
.Lz_go_e:
	s_waitcnt lgkmcnt(0)
	v_mfma_f32_32x32x16_bf16 v[64:79], v[204:207], v[160:163], v[144:159]
	v_exp_f32_e32 v112, v112
	v_exp_f32_e32 v113, v113
	v_add_f32_e32 v212, v110, v212
	v_add_f32_e32 v212, v111, v212
	v_mfma_f32_32x32x16_bf16 v[80:95], v[200:203], v[160:163], v[144:159]
	v_exp_f32_e32 v114, v114
	v_exp_f32_e32 v115, v115
	s_branch .Lk2_e

; #define FLAS __attribute__((address_space(3)))
; #define FA_SB() __builtin_amdgcn_sched_barrier(0)
; #define FA_EXP2(J, PX, R) do { const float e0_ = __builtin_amdgcn_exp2f(PX[R]), e1_ = __builtin_amdgcn_exp2f(PX[(R) + 1]); ps += e0_; ps += e1_; PWN[(J) >> 2][(J) & 3] = cvtpk(e0_, e1_); } while (0)
; __device__ __forceinline__ void attn_unit_a(FLAS unsigned char* lds, const Unit u) {
;     ...
;         if (ziN) { pN0 = __builtin_amdgcn_mfma_f32_32x32x16_bf16(kf[0], qr[0], z16, 0, 0, 0); FA_EXP2(8, pC1, 0); FA_SB(); pN1 = __builtin_amdgcn_mfma_f32_32x32x16_bf16(kf[1], qr[0], z16, 0, 0, 0); }
;         else { pN0 = __builtin_amdgcn_mfma_f32_32x32x16_bf16(kf[0], qr[0], pN0, 0, 0, 0); FA_EXP2(8, pC1, 0); FA_SB(); pN1 = __builtin_amdgcn_mfma_f32_32x32x16_bf16(kf[1], qr[0], pN1, 0, 0, 0); }
;         kf[0] = FA_KF(2, 0); kf[1] = FA_KF(2, 1); FA_EXP2(9, pC1, 2); FA_SB();
;         pN0 = __builtin_amdgcn_mfma_f32_32x32x16_bf16(kf[2], qr[1], pN0, 0, 0, 0); FA_EXP2(10, pC1, 4); FA_SB();
;         pN1 = __builtin_amdgcn_mfma_f32_32x32x16_bf16(kf[3], qr[1], pN1, 0, 0, 0); kf[2] = FA_KF(3, 0); kf[3] = FA_KF(3, 1); FA_EXP2(11, pC1, 6); FA_SB();
;         pN0 = __builtin_amdgcn_mfma_f32_32x32x16_bf16(kf[0], qr[2], pN0, 0, 0, 0); FA_EXP2(12, pC1, 8); FA_SB();
;         pN1 = __builtin_amdgcn_mfma_f32_32x32x16_bf16(kf[1], qr[2], pN1, 0, 0, 0); FA_EXP2(13, pC1, 10); FA_SB();
;         pN0 = __builtin_amdgcn_mfma_f32_32x32x16_bf16(kf[2], qr[3], pN0, 0, 0, 0); FA_EXP2(14, pC1, 12); FA_SB();
;         pN1 = __builtin_amdgcn_mfma_f32_32x32x16_bf16(kf[3], qr[3], pN1, 0, 0, 0); FA_EXP2(15, pC1, 14); FA_SB();
;     ...
;         lsum += ps; cbC = cbN;
;         if (i + 2 < NT) { *(FLAS u32x4*)(lds + LA_K + (i & 1) * KBUF + kdst) = kreg;
; #pragma unroll
;             for (int j = 0; j < 2; ++j) { *(FLAS u32x2*)(lds + LA_V + ((i + 2) & 3) * VBUF + vdst + j * 64 * VPITCH) = (u32x2){vreg[j].x, vreg[j].y}; *(FLAS u32x2*)(lds + LA_V + ((i + 2) & 3) * VBUF + vdst + j * 64 * VPITCH + 16) = (u32x2){vreg[j].z, vreg[j].w}; } }
.Lk2_e:
	ds_read_b128 v[128:131], v249 offset:8192
	ds_read_b128 v[132:135], v249 offset:8704
	s_add_i32 s34, s19, 2
	v_mfma_f32_32x32x16_bf16 v[64:79], v[196:199], v[164:167], v[64:79]
	v_exp_f32_e32 v116, v116
	v_exp_f32_e32 v117, v117
	v_mfma_f32_32x32x16_bf16 v[80:95], v[192:195], v[164:167], v[80:95]
	ds_read_b128 v[136:139], v250 offset:8192
	ds_read_b128 v[140:143], v250 offset:8704
	v_exp_f32_e32 v118, v118
	v_exp_f32_e32 v119, v119
	s_waitcnt lgkmcnt(3)
	v_mfma_f32_32x32x16_bf16 v[64:79], v[128:131], v[168:171], v[64:79]
	v_exp_f32_e32 v120, v120
	v_exp_f32_e32 v121, v121
	s_waitcnt lgkmcnt(2)
	v_mfma_f32_32x32x16_bf16 v[80:95], v[132:135], v[168:171], v[80:95]
	v_exp_f32_e32 v122, v122
	v_exp_f32_e32 v123, v123
	s_waitcnt lgkmcnt(1)
	v_mfma_f32_32x32x16_bf16 v[64:79], v[136:139], v[172:175], v[64:79]
	v_exp_f32_e32 v124, v124
	v_exp_f32_e32 v125, v125
	s_waitcnt lgkmcnt(0)
	v_mfma_f32_32x32x16_bf16 v[80:95], v[140:143], v[172:175], v[80:95]
	v_exp_f32_e32 v126, v126
	v_exp_f32_e32 v127, v127
	s_andn2_b64 vcc, exec, s[0:1]
	s_cbranch_vccnz .LBB0_456
	s_and_b32 s0, s34, 2
	s_mulk_i32 s0, 0x4800
	v_add_u32_e32 v128, s0, v245
	v_add_u32_e32 v129, 0x4000, v128
	v_add_u32_e32 v128, 0x6000, v128
	s_waitcnt vmcnt(2)
	ds_write_b128 v225, v[176:179]
	s_waitcnt vmcnt(1)
	ds_write2_b64 v129, v[180:181], v[182:183] offset1:2
	s_waitcnt vmcnt(0)
	ds_write2_b64 v128, v[184:185], v[186:187] offset0:128 offset1:130

; #define FLAS __attribute__((address_space(3)))
; __device__ __forceinline__ void attn_unit_a(FLAS unsigned char* lds, const Unit u) {
;     ...
;         const int vsp = (i == 0) ? 0 : ((i - 1) & 3);
;         const FLAS unsigned char* vb_ = lds + LA_V + vsp * VBUF + r32 * VPITCH + hi * 16;
;         const FLAS unsigned char* kb = lds + LA_K + ((i + 1) & 1) * KBUF;
;     ...
;         u32x4 vr[3];
; #pragma unroll
;         for (int m = 0; m < 3; ++m) vr[m] = FA_VFRAG(m);
;         const float off = cbC - mrun;
;         FA_SB();
;         float ra, rb, rm;
;         FA_PVM(0); pC0[0] = fadd_s(pC0[0], off); pC1[0] = fadd_s(pC1[0], off); pC0[1] = fadd_s(pC0[1], off); pC1[1] = fadd_s(pC1[1], off); pC0[2] = fadd_s(pC0[2], off); pC1[2] = fadd_s(pC1[2], off); FA_SB();
;         FA_PVM(1); ra = __builtin_fmaxf(__builtin_fmaxf(pC0[0], pC0[1]), pC0[2]); rb = __builtin_fmaxf(__builtin_fmaxf(pC1[0], pC1[1]), pC1[2]); pC0[3] = fadd_s(pC0[3], off); pC1[3] = fadd_s(pC1[3], off); pC0[4] = fadd_s(pC0[4], off); pC1[4] = fadd_s(pC1[4], off); FA_SB();
;         FA_PVM(2); ra = __builtin_fmaxf(__builtin_fmaxf(ra, pC0[3]), pC0[4]); rb = __builtin_fmaxf(__builtin_fmaxf(rb, pC1[3]), pC1[4]); pC0[5] = fadd_s(pC0[5], off); pC1[5] = fadd_s(pC1[5], off); pC0[6] = fadd_s(pC0[6], off); pC1[6] = fadd_s(pC1[6], off); FA_SB();
;         FA_PVM(3); ra = __builtin_fmaxf(__builtin_fmaxf(ra, pC0[5]), pC0[6]); rb = __builtin_fmaxf(__builtin_fmaxf(rb, pC1[5]), pC1[6]); pC0[7] = fadd_s(pC0[7], off); pC1[7] = fadd_s(pC1[7], off); pC0[8] = fadd_s(pC0[8], off); pC1[8] = fadd_s(pC1[8], off); FA_SB();
;         FA_PVM(4); ra = __builtin_fmaxf(__builtin_fmaxf(ra, pC0[7]), pC0[8]); rb = __builtin_fmaxf(__builtin_fmaxf(rb, pC1[7]), pC1[8]); pC0[9] = fadd_s(pC0[9], off); pC1[9] = fadd_s(pC1[9], off); pC0[10] = fadd_s(pC0[10], off); pC1[10] = fadd_s(pC1[10], off); FA_SB();
;         FA_PVM(5); ra = __builtin_fmaxf(__builtin_fmaxf(ra, pC0[9]), pC0[10]); rb = __builtin_fmaxf(__builtin_fmaxf(rb, pC1[9]), pC1[10]); pC0[11] = fadd_s(pC0[11], off); pC1[11] = fadd_s(pC1[11], off); pC0[12] = fadd_s(pC0[12], off); pC1[12] = fadd_s(pC1[12], off); FA_SB();
;         FA_PVM(6); ra = __builtin_fmaxf(__builtin_fmaxf(ra, pC0[11]), pC0[12]); rb = __builtin_fmaxf(__builtin_fmaxf(rb, pC1[11]), pC1[12]); pC0[13] = fadd_s(pC0[13], off); pC1[13] = fadd_s(pC1[13], off); pC0[14] = fadd_s(pC0[14], off); pC1[14] = fadd_s(pC1[14], off); FA_SB();
.LBB0_460:
	s_and_b32 s0, s19, 2
	s_mulk_i32 s0, 0x4800
	v_add_u32_e32 v201, s0, v251
	v_cvt_pk_bf16_f32 v140, v96, v97
	v_cvt_pk_bf16_f32 v141, v98, v99
	v_cvt_pk_bf16_f32 v142, v100, v101
	v_cvt_pk_bf16_f32 v143, v102, v103
	ds_read_b128 v[128:131], v201 offset:16384
	ds_read_b128 v[132:135], v201 offset:20992
	ds_read_b128 v[136:139], v201 offset:25600
	s_waitcnt lgkmcnt(2)
	v_mfma_f32_32x32x16_bf16 v[48:63], v[128:131], v[140:143], v[48:63]
	ds_read_b128 v[128:131], v201 offset:30208
	v_max3_f32 v96, v64, v65, v66
	v_max3_f32 v97, v80, v81, v82
	v_cvt_pk_bf16_f32 v232, v104, v105
	v_cvt_pk_bf16_f32 v233, v106, v107
	v_add_f32_e32 v212, v112, v212
	v_add_f32_e32 v212, v113, v212
	s_waitcnt lgkmcnt(2)
	v_mfma_f32_32x32x16_bf16 v[32:47], v[132:135], v[140:143], v[32:47]
	ds_read_b128 v[132:135], v201 offset:16416
	v_max3_f32 v96, v96, v67, v68
	v_max3_f32 v97, v97, v83, v84
	v_cvt_pk_bf16_f32 v234, v108, v109
	v_cvt_pk_bf16_f32 v235, v110, v111
	v_add_f32_e32 v212, v114, v212
	v_add_f32_e32 v212, v115, v212
	s_waitcnt lgkmcnt(2)
	v_mfma_f32_32x32x16_bf16 v[16:31], v[136:139], v[140:143], v[16:31]
	ds_read_b128 v[136:139], v201 offset:21024
	v_max3_f32 v96, v96, v69, v70
	v_max3_f32 v97, v97, v85, v86
	v_add_f32_e32 v212, v116, v212
	v_add_f32_e32 v212, v117, v212
	s_waitcnt lgkmcnt(2)
	v_mfma_f32_32x32x16_bf16 v[0:15], v[128:131], v[140:143], v[0:15]
	ds_read_b128 v[128:131], v201 offset:25632
	v_max3_f32 v96, v96, v71, v72
	v_max3_f32 v97, v97, v87, v88
	v_add_f32_e32 v212, v118, v212
	v_add_f32_e32 v212, v119, v212
	s_waitcnt lgkmcnt(2)
	v_mfma_f32_32x32x16_bf16 v[48:63], v[132:135], v[232:235], v[48:63]
	ds_read_b128 v[132:135], v201 offset:30240
	v_max3_f32 v96, v96, v73, v74
	v_max3_f32 v97, v97, v89, v90
	v_cvt_pk_bf16_f32 v140, v112, v113
	v_cvt_pk_bf16_f32 v141, v114, v115
	v_add_f32_e32 v212, v120, v212
	v_add_f32_e32 v212, v121, v212
	s_waitcnt lgkmcnt(2)
	v_mfma_f32_32x32x16_bf16 v[32:47], v[136:139], v[232:235], v[32:47]
	ds_read_b128 v[136:139], v201 offset:16448
	v_max3_f32 v96, v96, v75, v76
	v_max3_f32 v97, v97, v91, v92
	v_cvt_pk_bf16_f32 v142, v116, v117
	v_cvt_pk_bf16_f32 v143, v118, v119
	v_add_f32_e32 v212, v122, v212
	v_add_f32_e32 v212, v123, v212
	s_waitcnt lgkmcnt(2)
	v_mfma_f32_32x32x16_bf16 v[16:31], v[128:131], v[232:235], v[16:31]
	ds_read_b128 v[128:131], v201 offset:21056
	v_max3_f32 v96, v96, v77, v78
	v_max3_f32 v97, v97, v93, v94
	v_add_f32_e32 v212, v124, v212
	v_add_f32_e32 v212, v125, v212
	s_waitcnt lgkmcnt(2)
	v_mfma_f32_32x32x16_bf16 v[0:15], v[132:135], v[232:235], v[0:15]
	ds_read_b128 v[132:135], v201 offset:25664
	v_max3_f32 v96, v96, v97, v79
	v_max_f32_e32 v96, v96, v95
	v_add_f32_e32 v212, v126, v212
	v_add_f32_e32 v212, v127, v212
	v_mov_b32_e32 v97, v96
	s_nop 1
	v_permlane32_swap_b32 v96, v97
	s_nop 1
	s_nop 0
	v_max_f32_e32 v96, v96, v97
	v_cmp_lt_f32_e32 vcc, s39, v96
	s_cmp_lg_u64 vcc, 0
	s_cselect_b64 s[0:1], -1, 0
	s_cbranch_vccz .LBB0_462
	v_max_f32_e32 v96, v96, v96
	v_max_f32_e32 v96, 0, v96
	v_exp_f32_e64 v226, -v96
	v_add_f32_e32 v211, v211, v96
	v_sub_f32_e32 v64, v64, v96
	v_sub_f32_e32 v65, v65, v96
	v_mul_f32_e32 v212, v212, v226
	v_sub_f32_e32 v66, v66, v96
	v_sub_f32_e32 v67, v67, v96
	v_sub_f32_e32 v68, v68, v96
	v_sub_f32_e32 v69, v69, v96
	v_sub_f32_e32 v70, v70, v96
	v_sub_f32_e32 v71, v71, v96
	v_sub_f32_e32 v72, v72, v96
	v_sub_f32_e32 v73, v73, v96
	v_sub_f32_e32 v74, v74, v96
	v_sub_f32_e32 v75, v75, v96
	v_sub_f32_e32 v76, v76, v96
	v_sub_f32_e32 v77, v77, v96
	v_sub_f32_e32 v78, v78, v96
	v_sub_f32_e32 v79, v79, v96
	v_sub_f32_e32 v80, v80, v96
	v_sub_f32_e32 v81, v81, v96
	v_sub_f32_e32 v82, v82, v96
	v_sub_f32_e32 v83, v83, v96
	v_sub_f32_e32 v84, v84, v96
	v_sub_f32_e32 v85, v85, v96
	v_sub_f32_e32 v86, v86, v96
	v_sub_f32_e32 v87, v87, v96
	v_sub_f32_e32 v88, v88, v96
	v_sub_f32_e32 v89, v89, v96
	v_sub_f32_e32 v90, v90, v96
	v_sub_f32_e32 v91, v91, v96
	v_sub_f32_e32 v92, v92, v96
	v_sub_f32_e32 v93, v93, v96
	v_sub_f32_e32 v94, v94, v96
	v_sub_f32_e32 v95, v95, v96

; #define FA_SB() __builtin_amdgcn_sched_barrier(0)
; #define FA_EXP2(J, PX, R) do { const float e0_ = __builtin_amdgcn_exp2f(PX[R]), e1_ = __builtin_amdgcn_exp2f(PX[(R) + 1]); ps += e0_; ps += e1_; PWN[(J) >> 2][(J) & 3] = cvtpk(e0_, e1_); } while (0)
; __device__ __forceinline__ void attn_unit_a(FLAS unsigned char* lds, const Unit u) {
;     ...
;         float cbN; bool ziN; const int inx = (i + 1 < NT) ? i + 1 : NT - 1;
;         FA_BIAS(inx, pN0, pN1, cbN, ziN);
;         FA_SB();
;         if (ziN) { pN0 = __builtin_amdgcn_mfma_f32_32x32x16_bf16(kf[0], qr[0], z16, 0, 0, 0); FA_EXP2(8, pC1, 0); FA_SB(); pN1 = __builtin_amdgcn_mfma_f32_32x32x16_bf16(kf[1], qr[0], z16, 0, 0, 0); }
;         else { pN0 = __builtin_amdgcn_mfma_f32_32x32x16_bf16(kf[0], qr[0], pN0, 0, 0, 0); FA_EXP2(8, pC1, 0); FA_SB(); pN1 = __builtin_amdgcn_mfma_f32_32x32x16_bf16(kf[1], qr[0], pN1, 0, 0, 0); }
;         kf[0] = FA_KF(2, 0); kf[1] = FA_KF(2, 1); FA_EXP2(9, pC1, 2); FA_SB();
;         pN0 = __builtin_amdgcn_mfma_f32_32x32x16_bf16(kf[2], qr[1], pN0, 0, 0, 0); FA_EXP2(10, pC1, 4); FA_SB();
.Lz_go_o:
	s_waitcnt lgkmcnt(0)
	v_mfma_f32_32x32x16_bf16 v[96:111], v[200:203], v[160:163], v[144:159]
	v_exp_f32_e32 v80, v80
	v_exp_f32_e32 v81, v81
	v_add_f32_e32 v212, v78, v212
	v_add_f32_e32 v212, v79, v212
	v_mfma_f32_32x32x16_bf16 v[112:127], v[196:199], v[160:163], v[144:159]
	v_exp_f32_e32 v82, v82
	v_exp_f32_e32 v83, v83
	s_branch .Lk2_o

; #define FLAS __attribute__((address_space(3)))
; #define FA_SB() __builtin_amdgcn_sched_barrier(0)
; #define FA_EXP2(J, PX, R) do { const float e0_ = __builtin_amdgcn_exp2f(PX[R]), e1_ = __builtin_amdgcn_exp2f(PX[(R) + 1]); ps += e0_; ps += e1_; PWN[(J) >> 2][(J) & 3] = cvtpk(e0_, e1_); } while (0)
; __device__ __forceinline__ void attn_unit_a(FLAS unsigned char* lds, const Unit u) {
;     ...
;         if (ziN) { pN0 = __builtin_amdgcn_mfma_f32_32x32x16_bf16(kf[0], qr[0], z16, 0, 0, 0); FA_EXP2(8, pC1, 0); FA_SB(); pN1 = __builtin_amdgcn_mfma_f32_32x32x16_bf16(kf[1], qr[0], z16, 0, 0, 0); }
;         else { pN0 = __builtin_amdgcn_mfma_f32_32x32x16_bf16(kf[0], qr[0], pN0, 0, 0, 0); FA_EXP2(8, pC1, 0); FA_SB(); pN1 = __builtin_amdgcn_mfma_f32_32x32x16_bf16(kf[1], qr[0], pN1, 0, 0, 0); }
;         kf[0] = FA_KF(2, 0); kf[1] = FA_KF(2, 1); FA_EXP2(9, pC1, 2); FA_SB();
;         pN0 = __builtin_amdgcn_mfma_f32_32x32x16_bf16(kf[2], qr[1], pN0, 0, 0, 0); FA_EXP2(10, pC1, 4); FA_SB();
;         pN1 = __builtin_amdgcn_mfma_f32_32x32x16_bf16(kf[3], qr[1], pN1, 0, 0, 0); kf[2] = FA_KF(3, 0); kf[3] = FA_KF(3, 1); FA_EXP2(11, pC1, 6); FA_SB();
;         pN0 = __builtin_amdgcn_mfma_f32_32x32x16_bf16(kf[0], qr[2], pN0, 0, 0, 0); FA_EXP2(12, pC1, 8); FA_SB();
;         pN1 = __builtin_amdgcn_mfma_f32_32x32x16_bf16(kf[1], qr[2], pN1, 0, 0, 0); FA_EXP2(13, pC1, 10); FA_SB();
;         pN0 = __builtin_amdgcn_mfma_f32_32x32x16_bf16(kf[2], qr[3], pN0, 0, 0, 0); FA_EXP2(14, pC1, 12); FA_SB();
;         pN1 = __builtin_amdgcn_mfma_f32_32x32x16_bf16(kf[3], qr[3], pN1, 0, 0, 0); FA_EXP2(15, pC1, 14); FA_SB();
;     ...
;         lsum += ps; cbC = cbN;
;         if (i + 2 < NT) { *(FLAS u32x4*)(lds + LA_K + (i & 1) * KBUF + kdst) = kreg;
; #pragma unroll
;             for (int j = 0; j < 2; ++j) { *(FLAS u32x2*)(lds + LA_V + ((i + 2) & 3) * VBUF + vdst + j * 64 * VPITCH) = (u32x2){vreg[j].x, vreg[j].y}; *(FLAS u32x2*)(lds + LA_V + ((i + 2) & 3) * VBUF + vdst + j * 64 * VPITCH + 16) = (u32x2){vreg[j].z, vreg[j].w}; } }
.Lk2_o:
	ds_read_b128 v[128:131], v249
	ds_read_b128 v[132:135], v249 offset:512
	v_mfma_f32_32x32x16_bf16 v[96:111], v[192:195], v[164:167], v[96:111]
	v_exp_f32_e32 v84, v84
	v_exp_f32_e32 v85, v85
	v_mfma_f32_32x32x16_bf16 v[112:127], v[188:191], v[164:167], v[112:127]
	ds_read_b128 v[136:139], v250
	ds_read_b128 v[140:143], v250 offset:512
	v_exp_f32_e32 v86, v86
	v_exp_f32_e32 v87, v87
	s_waitcnt lgkmcnt(3)
	v_mfma_f32_32x32x16_bf16 v[96:111], v[128:131], v[168:171], v[96:111]
	v_exp_f32_e32 v88, v88
	v_exp_f32_e32 v89, v89
	s_waitcnt lgkmcnt(2)
	v_mfma_f32_32x32x16_bf16 v[112:127], v[132:135], v[168:171], v[112:127]
	v_exp_f32_e32 v90, v90
	v_exp_f32_e32 v91, v91
	s_waitcnt lgkmcnt(1)
	v_mfma_f32_32x32x16_bf16 v[96:111], v[136:139], v[172:175], v[96:111]
	v_exp_f32_e32 v92, v92
	v_exp_f32_e32 v93, v93
	s_waitcnt lgkmcnt(0)
	v_mfma_f32_32x32x16_bf16 v[112:127], v[140:143], v[172:175], v[112:127]
	v_exp_f32_e32 v94, v94
	v_exp_f32_e32 v95, v95
	s_andn2_b64 vcc, exec, s[20:21]
	s_cbranch_vccnz .LBB0_476
	v_add_u32_e32 v128, s18, v245
	v_add_u32_e32 v129, 0x4000, v128
	v_add_u32_e32 v128, 0x6000, v128
	s_waitcnt vmcnt(2)
	ds_write_b128 v225, v[176:179] offset:8192
	s_waitcnt vmcnt(1)
	ds_write2_b64 v129, v[180:181], v[182:183] offset1:2
	s_waitcnt vmcnt(0)
	ds_write2_b64 v128, v[184:185], v[186:187] offset0:128 offset1:130

; __device__ __forceinline__ float xhalf_sum(float m) { unsigned a = __builtin_bit_cast(unsigned, m), b = a; xswap(a, b); return __builtin_bit_cast(float, a) + __builtin_bit_cast(float, b); }
; __device__ __forceinline__ void attn_unit_a(FLAS unsigned char* lds, const Unit u) {
;     ...
;     if (NT & 1) { FA_PVP((NT - 1) & 3, pwb); } else { FA_PVP((NT - 1) & 3, pwa); }
;     ...
;     const float inv = 1.0f / xhalf_sum(lsum);
;     bf16_t* op = u.O + (size_t)(u.tok0 + q) * u.ldo + 4 * hi;
;     if (u.comb) {
;         const float lam = *u.lamp, gsc = 1.0f - u.lam_init;
;         const bf16_t* o1p = u.O1 + (size_t)(u.tok0 + q) * 512 + 4 * hi;
;         float ss = 0.f;
; #pragma unroll
;         for (int db = 0; db < NDB; ++db)
; #pragma unroll
;             for (int g = 0; g < 4; ++g) {
;                 const unsigned long long w = __hip_atomic_load((const unsigned long long*)(o1p + db * 32 + 8 * g), __ATOMIC_RELAXED, __HIP_MEMORY_SCOPE_AGENT);
;                 const unsigned w0 = (unsigned)w, w1 = (unsigned)(w >> 32);
;                 const float a0 = __builtin_bit_cast(float, w0 << 16), a1 = __builtin_bit_cast(float, w0 & 0xffff0000u), a2 = __builtin_bit_cast(float, w1 << 16), a3 = __builtin_bit_cast(float, w1 & 0xffff0000u);
;                 const float x0 = a0 - lam * (o[db][4 * g] * inv), x1 = a1 - lam * (o[db][4 * g + 1] * inv), x2 = a2 - lam * (o[db][4 * g + 2] * inv), x3 = a3 - lam * (o[db][4 * g + 3] * inv);
.LBB0_479:
	v_add_f32_e32 v212, v80, v212
	v_add_f32_e32 v212, v81, v212
	v_add_f32_e32 v212, v82, v212
	v_add_f32_e32 v212, v83, v212
	v_add_f32_e32 v212, v84, v212
	v_add_f32_e32 v212, v85, v212
	v_add_f32_e32 v212, v86, v212
	v_add_f32_e32 v212, v87, v212
	v_add_f32_e32 v212, v88, v212
	v_add_f32_e32 v212, v89, v212
	v_add_f32_e32 v212, v90, v212
	v_add_f32_e32 v212, v91, v212
	v_add_f32_e32 v212, v92, v212
	v_add_f32_e32 v212, v93, v212
	v_add_f32_e32 v212, v94, v212
	v_add_f32_e32 v212, v95, v212
	v_cvt_pk_bf16_f32 v196, v72, v73
	v_cvt_pk_bf16_f32 v197, v74, v75
	v_cvt_pk_bf16_f32 v198, v76, v77
	v_cvt_pk_bf16_f32 v199, v78, v79
	v_cvt_pk_bf16_f32 v192, v80, v81
	v_cvt_pk_bf16_f32 v193, v82, v83
	v_cvt_pk_bf16_f32 v194, v84, v85
	v_cvt_pk_bf16_f32 v195, v86, v87
	v_cvt_pk_bf16_f32 v188, v88, v89
	v_cvt_pk_bf16_f32 v189, v90, v91
	v_cvt_pk_bf16_f32 v190, v92, v93
	v_cvt_pk_bf16_f32 v191, v94, v95
	v_readlane_b32 s12, v254, 48
	s_lshl_b32 s0, s26, 1
	s_add_u32 s0, s16, s0
	v_add3_u32 v82, s12, v246, v224
	ds_read_b128 v[64:67], v82
	ds_read_b128 v[68:71], v82 offset:4608
	ds_read_b128 v[72:75], v82 offset:9216
	ds_read_b128 v[76:79], v82 offset:13824
	s_addc_u32 s1, s17, 0
	s_cmp_eq_u32 s44, 0
	v_mov_b32_e32 v240, v213
	s_cselect_b32 s4, s0, s45
	s_cselect_b32 s5, s1, s46
	s_movk_i32 s12, 0x200
	s_cselect_b32 s12, s12, 0x600
	s_cmp_lg_u32 s44, 0
	v_mov_b32_e32 v80, s4
	v_mov_b32_e32 v81, s5
	s_waitcnt lgkmcnt(3)
	v_mfma_f32_32x32x16_bf16 v[48:63], v[64:67], v[204:207], v[48:63]
	ds_read_b128 v[64:67], v82 offset:32
	s_waitcnt lgkmcnt(3)
	v_mfma_f32_32x32x16_bf16 v[32:47], v[68:71], v[204:207], v[32:47]
	ds_read_b128 v[68:71], v82 offset:4640
	s_waitcnt lgkmcnt(3)
	v_mfma_f32_32x32x16_bf16 v[16:31], v[72:75], v[204:207], v[16:31]
	ds_read_b128 v[72:75], v82 offset:9248
	s_waitcnt lgkmcnt(3)
	v_mfma_f32_32x32x16_bf16 v[0:15], v[76:79], v[204:207], v[0:15]
	ds_read_b128 v[76:79], v82 offset:13856
	s_waitcnt lgkmcnt(3)
	v_mfma_f32_32x32x16_bf16 v[48:63], v[64:67], v[196:199], v[48:63]
	ds_read_b128 v[64:67], v82 offset:64
	s_waitcnt lgkmcnt(3)
	v_mfma_f32_32x32x16_bf16 v[32:47], v[68:71], v[196:199], v[32:47]
	ds_read_b128 v[68:71], v82 offset:4672
	s_waitcnt lgkmcnt(3)
	v_mfma_f32_32x32x16_bf16 v[16:31], v[72:75], v[196:199], v[16:31]
	ds_read_b128 v[72:75], v82 offset:9280
	s_waitcnt lgkmcnt(3)
	v_mfma_f32_32x32x16_bf16 v[0:15], v[76:79], v[196:199], v[0:15]
	ds_read_b128 v[76:79], v82 offset:13888
	s_waitcnt lgkmcnt(3)
	v_mfma_f32_32x32x16_bf16 v[48:63], v[64:67], v[192:195], v[48:63]
	ds_read_b128 v[64:67], v82 offset:96
	s_waitcnt lgkmcnt(3)
	v_mfma_f32_32x32x16_bf16 v[32:47], v[68:71], v[192:195], v[32:47]
	ds_read_b128 v[68:71], v82 offset:4704
	s_waitcnt lgkmcnt(3)
	v_mfma_f32_32x32x16_bf16 v[16:31], v[72:75], v[192:195], v[16:31]
	ds_read_b128 v[72:75], v82 offset:9312
	s_waitcnt lgkmcnt(3)
	v_mfma_f32_32x32x16_bf16 v[0:15], v[76:79], v[192:195], v[0:15]
	ds_read_b128 v[76:79], v82 offset:13920
	s_waitcnt lgkmcnt(3)
	v_mfma_f32_32x32x16_bf16 v[48:63], v[64:67], v[188:191], v[48:63]
	s_waitcnt lgkmcnt(2)
	v_mfma_f32_32x32x16_bf16 v[32:47], v[68:71], v[188:191], v[32:47]
	s_waitcnt lgkmcnt(1)
	v_mfma_f32_32x32x16_bf16 v[16:31], v[72:75], v[188:191], v[16:31]
	s_waitcnt lgkmcnt(0)
	v_mfma_f32_32x32x16_bf16 v[0:15], v[76:79], v[188:191], v[0:15]
	v_mov_b32_e32 v64, v212
	s_nop 1
	v_permlane32_swap_b32 v212, v64
	s_nop 1
	v_lshlrev_b32_e32 v208, 3, v243
	v_add_f32_e32 v64, v212, v64
	v_div_scale_f32 v65, s[4:5], v64, v64, 1.0
	v_rcp_f32_e32 v66, v65
	v_div_scale_f32 v67, vcc, 1.0, v64, 1.0
	v_mov_b32_e32 v244, v227
	v_fma_f32 v68, -v65, v66, 1.0
	v_fmac_f32_e32 v66, v68, v66
	v_mul_f32_e32 v68, v67, v66
	v_fma_f32 v69, -v65, v68, v67
	v_fmac_f32_e32 v68, v69, v66
	v_fma_f32 v65, -v65, v68, v67
	v_div_fmas_f32 v65, v65, v66, v68
	v_div_fixup_f32 v66, v65, v64, 1.0
	v_mad_i64_i32 v[64:65], s[4:5], s12, v222, 0
	v_lshl_add_u64 v[64:65], v[64:65], 1, v[80:81]
	v_lshl_add_u64 v[64:65], v[64:65], 0, v[208:209]
	s_mov_b64 s[4:5], -1
	s_cbranch_scc0 .LBB0_481
	v_lshlrev_b32_e32 v67, 2, v243
	v_lshlrev_b64 v[68:69], 10, v[222:223]
	v_lshl_add_u64 v[68:69], s[0:1], 0, v[68:69]
	v_lshlrev_b32_e32 v208, 1, v67
	v_lshl_add_u64 v[68:69], v[68:69], 0, v[208:209]
	global_load_dword v70, v209, s[6:7]
	global_load_dwordx2 v[72:73], v[68:69], off sc1
	global_load_dwordx2 v[74:75], v[68:69], off offset:16 sc1
	global_load_dwordx2 v[76:77], v[68:69], off offset:32 sc1
	global_load_dwordx2 v[78:79], v[68:69], off offset:48 sc1
	global_load_dwordx2 v[80:81], v[68:69], off offset:64 sc1
	global_load_dwordx2 v[82:83], v[68:69], off offset:80 sc1
	global_load_dwordx2 v[84:85], v[68:69], off offset:96 sc1
	global_load_dwordx2 v[86:87], v[68:69], off offset:112 sc1
	global_load_dwordx2 v[88:89], v[68:69], off offset:128 sc1
	global_load_dwordx2 v[90:91], v[68:69], off offset:144 sc1
	global_load_dwordx2 v[92:93], v[68:69], off offset:160 sc1
	global_load_dwordx2 v[94:95], v[68:69], off offset:176 sc1
	global_load_dwordx2 v[96:97], v[68:69], off offset:192 sc1
	global_load_dwordx2 v[98:99], v[68:69], off offset:208 sc1
	global_load_dwordx2 v[100:101], v[68:69], off offset:224 sc1
	s_nop 0
	global_load_dwordx2 v[68:69], v[68:69], off offset:240 sc1
	v_lshlrev_b32_e32 v67, 2, v67
	s_waitcnt vmcnt(15)
	v_lshlrev_b32_e32 v102, 16, v72
	v_and_b32_e32 v103, 0xffff0000, v72
	v_lshlrev_b32_e32 v72, 16, v73
	s_waitcnt vmcnt(12)
	v_lshlrev_b32_e32 v108, 16, v78
	v_and_b32_e32 v109, 0xffff0000, v78
	v_lshlrev_b32_e32 v110, 16, v79
	v_and_b32_e32 v111, 0xffff0000, v79
	v_pk_mul_f32 v[78:79], v[14:15], v[66:67] op_sel_hi:[1,0]
	v_and_b32_e32 v73, 0xffff0000, v73
	s_waitcnt vmcnt(9)
; __device__ __forceinline__ void attn_unit_a(FLAS unsigned char* lds, const Unit u) {
;     ...
;             for (int g = 0; g < 4; ++g) {
;                 const unsigned long long w = __hip_atomic_load((const unsigned long long*)(o1p + db * 32 + 8 * g), __ATOMIC_RELAXED, __HIP_MEMORY_SCOPE_AGENT);
;                 const unsigned w0 = (unsigned)w, w1 = (unsigned)(w >> 32);
;                 const float a0 = __builtin_bit_cast(float, w0 << 16), a1 = __builtin_bit_cast(float, w0 & 0xffff0000u), a2 = __builtin_bit_cast(float, w1 << 16), a3 = __builtin_bit_cast(float, w1 & 0xffff0000u);
;                 const float x0 = a0 - lam * (o[db][4 * g] * inv), x1 = a1 - lam * (o[db][4 * g + 1] * inv), x2 = a2 - lam * (o[db][4 * g + 2] * inv), x3 = a3 - lam * (o[db][4 * g + 3] * inv);
;                 o[db][4 * g] = x0; o[db][4 * g + 1] = x1; o[db][4 * g + 2] = x2; o[db][4 * g + 3] = x3; ss += (x0 * x0 + x1 * x1) + (x2 * x2 + x3 * x3); }
	v_lshlrev_b32_e32 v142, 16, v84
	v_and_b32_e32 v143, 0xffff0000, v84
	v_lshlrev_b32_e32 v144, 16, v85
	v_and_b32_e32 v145, 0xffff0000, v85
	v_lshlrev_b32_e32 v116, 16, v80
	v_and_b32_e32 v117, 0xffff0000, v80
	s_waitcnt vmcnt(0)
	v_lshlrev_b32_e32 v114, 16, v68
	v_and_b32_e32 v115, 0xffff0000, v68
	v_lshlrev_b32_e32 v68, 16, v69
	v_and_b32_e32 v69, 0xffff0000, v69
	v_pk_fma_f32 v[68:69], v[78:79], v[70:71], v[68:69] op_sel_hi:[1,0,1] neg_lo:[1,0,0] neg_hi:[1,0,0]
	v_pk_mul_f32 v[78:79], v[50:51], v[66:67] op_sel_hi:[1,0]
	v_lshlrev_b32_e32 v104, 16, v74
	v_pk_fma_f32 v[72:73], v[78:79], v[70:71], v[72:73] op_sel_hi:[1,0,1] neg_lo:[1,0,0] neg_hi:[1,0,0]
	v_and_b32_e32 v105, 0xffff0000, v74
	v_mul_f32_e32 v78, v73, v73
	v_pk_fma_f32 v[84:85], v[72:73], v[72:73], v[78:79] op_sel_hi:[1,1,0]
	v_pk_mul_f32 v[78:79], v[48:49], v[66:67] op_sel_hi:[1,0]
	v_lshlrev_b32_e32 v74, 16, v75
	v_pk_fma_f32 v[78:79], v[78:79], v[70:71], v[102:103] op_sel_hi:[1,0,1] neg_lo:[1,0,0] neg_hi:[1,0,0]
	v_and_b32_e32 v75, 0xffff0000, v75
	v_mul_f32_e32 v80, v79, v79
	v_lshlrev_b32_e32 v136, 16, v81
	v_and_b32_e32 v137, 0xffff0000, v81
	v_lshlrev_b32_e32 v146, 16, v86
	v_and_b32_e32 v147, 0xffff0000, v86
	v_lshlrev_b32_e32 v148, 16, v87
	v_and_b32_e32 v149, 0xffff0000, v87
	v_pk_fma_f32 v[86:87], v[78:79], v[78:79], v[80:81] op_sel_hi:[1,1,0]
	v_pk_mul_f32 v[80:81], v[54:55], v[66:67] op_sel_hi:[1,0]
	v_lshlrev_b32_e32 v150, 16, v88
	v_pk_fma_f32 v[74:75], v[80:81], v[70:71], v[74:75] op_sel_hi:[1,0,1] neg_lo:[1,0,0] neg_hi:[1,0,0]
	v_and_b32_e32 v151, 0xffff0000, v88
	v_mul_f32_e32 v80, v75, v75
	v_lshlrev_b32_e32 v152, 16, v89
	v_and_b32_e32 v153, 0xffff0000, v89
	v_pk_fma_f32 v[88:89], v[74:75], v[74:75], v[80:81] op_sel_hi:[1,1,0]
	v_pk_mul_f32 v[80:81], v[52:53], v[66:67] op_sel_hi:[1,0]
	v_lshlrev_b32_e32 v138, 16, v82
	v_pk_fma_f32 v[80:81], v[80:81], v[70:71], v[104:105] op_sel_hi:[1,0,1] neg_lo:[1,0,0] neg_hi:[1,0,0]
	v_and_b32_e32 v139, 0xffff0000, v82
	v_mul_f32_e32 v82, v81, v81
	v_lshlrev_b32_e32 v106, 16, v76
	v_and_b32_e32 v107, 0xffff0000, v76
	v_lshlrev_b32_e32 v76, 16, v77
	v_and_b32_e32 v77, 0xffff0000, v77
	v_lshlrev_b32_e32 v140, 16, v83
	v_and_b32_e32 v141, 0xffff0000, v83
	v_lshlrev_b32_e32 v154, 16, v90
	v_and_b32_e32 v155, 0xffff0000, v90
	v_lshlrev_b32_e32 v156, 16, v91
	v_and_b32_e32 v157, 0xffff0000, v91
	v_pk_fma_f32 v[90:91], v[80:81], v[80:81], v[82:83] op_sel_hi:[1,1,0]
	v_pk_mul_f32 v[82:83], v[58:59], v[66:67] op_sel_hi:[1,0]
	v_lshlrev_b32_e32 v118, 16, v92
	v_pk_fma_f32 v[76:77], v[82:83], v[70:71], v[76:77] op_sel_hi:[1,0,1] neg_lo:[1,0,0] neg_hi:[1,0,0]
	v_pk_mul_f32 v[82:83], v[56:57], v[66:67] op_sel_hi:[1,0]
	v_and_b32_e32 v119, 0xffff0000, v92
	v_pk_fma_f32 v[82:83], v[82:83], v[70:71], v[106:107] op_sel_hi:[1,0,1] neg_lo:[1,0,0] neg_hi:[1,0,0]
	v_lshlrev_b32_e32 v158, 16, v93
	v_and_b32_e32 v159, 0xffff0000, v93
	v_lshlrev_b32_e32 v122, 16, v94
	v_and_b32_e32 v123, 0xffff0000, v94
	v_lshlrev_b32_e32 v112, 16, v95
	v_and_b32_e32 v113, 0xffff0000, v95
	v_pk_mul_f32 v[92:93], v[76:77], v[76:77]
	v_pk_mul_f32 v[94:95], v[82:83], v[82:83]
	v_mov_b32_e32 v91, v92
	v_mov_b32_e32 v89, v93
	v_mov_b32_e32 v87, v94
	v_mov_b32_e32 v85, v95
	v_pk_add_f32 v[88:89], v[90:91], v[88:89]
	v_pk_add_f32 v[84:85], v[86:87], v[84:85]
	v_lshlrev_b32_e32 v132, 16, v96
	v_pk_add_f32 v[84:85], v[84:85], v[88:89]
	v_and_b32_e32 v133, 0xffff0000, v96
	v_lshlrev_b32_e32 v124, 16, v97
	v_and_b32_e32 v125, 0xffff0000, v97
	v_pk_add_f32 v[96:97], v[84:85], v[84:85] op_sel:[0,1] op_sel_hi:[1,0]
	v_pk_mul_f32 v[84:85], v[62:63], v[66:67] op_sel_hi:[1,0]
	v_pk_mul_f32 v[86:87], v[60:61], v[66:67] op_sel_hi:[1,0]
	v_pk_fma_f32 v[84:85], v[84:85], v[70:71], v[110:111] op_sel_hi:[1,0,1] neg_lo:[1,0,0] neg_hi:[1,0,0]
	v_pk_fma_f32 v[90:91], v[86:87], v[70:71], v[108:109] op_sel_hi:[1,0,1] neg_lo:[1,0,0] neg_hi:[1,0,0]
	v_mov_b32_e32 v89, v85
	v_mov_b32_e32 v88, v91
	v_mov_b32_e32 v86, v90
	v_mov_b32_e32 v87, v84
	v_pk_mul_f32 v[88:89], v[88:89], v[88:89]
	v_lshlrev_b32_e32 v134, 16, v98
	v_pk_fma_f32 v[86:87], v[86:87], v[86:87], v[88:89]
	v_and_b32_e32 v135, 0xffff0000, v98
	v_lshlrev_b32_e32 v126, 16, v99
	v_and_b32_e32 v127, 0xffff0000, v99
	v_pk_add_f32 v[98:99], v[86:87], v[86:87] op_sel:[0,1] op_sel_hi:[1,0]
	v_pk_mul_f32 v[86:87], v[34:35], v[66:67] op_sel_hi:[1,0]
	v_lshlrev_b32_e32 v120, 16, v100
	v_pk_fma_f32 v[86:87], v[86:87], v[70:71], v[136:137] op_sel_hi:[1,0,1] neg_lo:[1,0,0] neg_hi:[1,0,0]
	v_and_b32_e32 v121, 0xffff0000, v100
	v_mul_f32_e32 v88, v87, v87
	v_lshlrev_b32_e32 v130, 16, v101
	v_and_b32_e32 v131, 0xffff0000, v101
	v_pk_fma_f32 v[100:101], v[86:87], v[86:87], v[88:89] op_sel_hi:[1,1,0]
	v_pk_mul_f32 v[88:89], v[32:33], v[66:67] op_sel_hi:[1,0]
	v_pk_mul_f32 v[94:95], v[36:37], v[66:67] op_sel_hi:[1,0]
	v_pk_fma_f32 v[92:93], v[88:89], v[70:71], v[116:117] op_sel_hi:[1,0,1] neg_lo:[1,0,0] neg_hi:[1,0,0]
	v_pk_fma_f32 v[94:95], v[94:95], v[70:71], v[138:139] op_sel_hi:[1,0,1] neg_lo:[1,0,0] neg_hi:[1,0,0]
	v_mul_f32_e32 v88, v93, v93
	v_pk_fma_f32 v[102:103], v[92:93], v[92:93], v[88:89] op_sel_hi:[1,1,0]
	v_pk_mul_f32 v[88:89], v[38:39], v[66:67] op_sel_hi:[1,0]
	v_pk_mul_f32 v[106:107], v[94:95], v[94:95]
	v_pk_fma_f32 v[88:89], v[88:89], v[70:71], v[140:141] op_sel_hi:[1,0,1] neg_lo:[1,0,0] neg_hi:[1,0,0]
	v_mov_b32_e32 v97, v106
	v_pk_mul_f32 v[104:105], v[88:89], v[88:89]
	v_mov_b32_e32 v99, v107
	v_mov_b32_e32 v103, v104
	v_mov_b32_e32 v101, v105
	v_pk_add_f32 v[100:101], v[102:103], v[100:101]
	v_pk_add_f32 v[96:97], v[96:97], v[98:99]
	v_pk_mul_f32 v[98:99], v[40:41], v[66:67] op_sel_hi:[1,0]
	v_pk_add_f32 v[96:97], v[96:97], v[100:101]
; __device__ __forceinline__ void attn_unit_a(FLAS unsigned char* lds, const Unit u) {
;     ...
;             for (int g = 0; g < 4; ++g) {
;                 const unsigned long long w = __hip_atomic_load((const unsigned long long*)(o1p + db * 32 + 8 * g), __ATOMIC_RELAXED, __HIP_MEMORY_SCOPE_AGENT);
;                 const unsigned w0 = (unsigned)w, w1 = (unsigned)(w >> 32);
;                 const float a0 = __builtin_bit_cast(float, w0 << 16), a1 = __builtin_bit_cast(float, w0 & 0xffff0000u), a2 = __builtin_bit_cast(float, w1 << 16), a3 = __builtin_bit_cast(float, w1 & 0xffff0000u);
;                 const float x0 = a0 - lam * (o[db][4 * g] * inv), x1 = a1 - lam * (o[db][4 * g + 1] * inv), x2 = a2 - lam * (o[db][4 * g + 2] * inv), x3 = a3 - lam * (o[db][4 * g + 3] * inv);
;                 o[db][4 * g] = x0; o[db][4 * g + 1] = x1; o[db][4 * g + 2] = x2; o[db][4 * g + 3] = x3; ss += (x0 * x0 + x1 * x1) + (x2 * x2 + x3 * x3); }
	v_pk_fma_f32 v[102:103], v[98:99], v[70:71], v[142:143] op_sel_hi:[1,0,1] neg_lo:[1,0,0] neg_hi:[1,0,0]
	v_pk_add_f32 v[108:109], v[96:97], v[96:97] op_sel:[0,1] op_sel_hi:[1,0]
	v_pk_mul_f32 v[96:97], v[42:43], v[66:67] op_sel_hi:[1,0]
	v_mov_b32_e32 v100, v103
	v_pk_fma_f32 v[96:97], v[96:97], v[70:71], v[144:145] op_sel_hi:[1,0,1] neg_lo:[1,0,0] neg_hi:[1,0,0]
	v_mov_b32_e32 v98, v102
	v_mov_b32_e32 v101, v97
	v_mov_b32_e32 v99, v96
	v_pk_mul_f32 v[100:101], v[100:101], v[100:101]
	v_pk_mul_f32 v[104:105], v[16:17], v[66:67] op_sel_hi:[1,0]
	v_pk_fma_f32 v[98:99], v[98:99], v[98:99], v[100:101]
	v_pk_fma_f32 v[104:105], v[104:105], v[70:71], v[150:151] op_sel_hi:[1,0,1] neg_lo:[1,0,0] neg_hi:[1,0,0]
	v_pk_add_f32 v[110:111], v[98:99], v[98:99] op_sel:[0,1] op_sel_hi:[1,0]
	v_pk_mul_f32 v[98:99], v[46:47], v[66:67] op_sel_hi:[1,0]
	v_pk_mul_f32 v[140:141], v[104:105], v[104:105]
	v_pk_fma_f32 v[98:99], v[98:99], v[70:71], v[148:149] op_sel_hi:[1,0,1] neg_lo:[1,0,0] neg_hi:[1,0,0]
	v_mov_b32_e32 v109, v140
	v_mul_f32_e32 v100, v99, v99
	v_pk_fma_f32 v[116:117], v[98:99], v[98:99], v[100:101] op_sel_hi:[1,1,0]
	v_pk_mul_f32 v[100:101], v[44:45], v[66:67] op_sel_hi:[1,0]
	v_mov_b32_e32 v111, v141
	v_pk_fma_f32 v[106:107], v[100:101], v[70:71], v[146:147] op_sel_hi:[1,0,1] neg_lo:[1,0,0] neg_hi:[1,0,0]
	v_pk_add_f32 v[108:109], v[108:109], v[110:111]
	v_mul_f32_e32 v100, v107, v107
	v_pk_fma_f32 v[136:137], v[106:107], v[106:107], v[100:101] op_sel_hi:[1,1,0]
	v_pk_mul_f32 v[100:101], v[18:19], v[66:67] op_sel_hi:[1,0]
	v_pk_mul_f32 v[110:111], v[20:21], v[66:67] op_sel_hi:[1,0]
	v_pk_fma_f32 v[100:101], v[100:101], v[70:71], v[152:153] op_sel_hi:[1,0,1] neg_lo:[1,0,0] neg_hi:[1,0,0]
	v_pk_mul_f32 v[146:147], v[28:29], v[66:67] op_sel_hi:[1,0]
	v_pk_mul_f32 v[138:139], v[100:101], v[100:101]
	v_pk_mul_f32 v[142:143], v[24:25], v[66:67] op_sel_hi:[1,0]
	v_mov_b32_e32 v137, v138
	v_mov_b32_e32 v117, v139
	v_pk_add_f32 v[116:117], v[136:137], v[116:117]
	v_pk_fma_f32 v[122:123], v[146:147], v[70:71], v[122:123] op_sel_hi:[1,0,1] neg_lo:[1,0,0] neg_hi:[1,0,0]
	v_pk_add_f32 v[108:109], v[108:109], v[116:117]
	v_pk_fma_f32 v[116:117], v[110:111], v[70:71], v[154:155] op_sel_hi:[1,0,1] neg_lo:[1,0,0] neg_hi:[1,0,0]
	v_pk_add_f32 v[136:137], v[108:109], v[108:109] op_sel:[0,1] op_sel_hi:[1,0]
	v_pk_mul_f32 v[108:109], v[22:23], v[66:67] op_sel_hi:[1,0]
	v_mov_b32_e32 v138, v117
	v_pk_fma_f32 v[108:109], v[108:109], v[70:71], v[156:157] op_sel_hi:[1,0,1] neg_lo:[1,0,0] neg_hi:[1,0,0]
	v_mov_b32_e32 v110, v116
	v_mov_b32_e32 v139, v109
	v_mov_b32_e32 v111, v108
	v_pk_mul_f32 v[138:139], v[138:139], v[138:139]
	v_pk_fma_f32 v[118:119], v[142:143], v[70:71], v[118:119] op_sel_hi:[1,0,1] neg_lo:[1,0,0] neg_hi:[1,0,0]
	v_pk_fma_f32 v[110:111], v[110:111], v[110:111], v[138:139]
	v_pk_mul_f32 v[144:145], v[30:31], v[66:67] op_sel_hi:[1,0]
	v_pk_add_f32 v[138:139], v[110:111], v[110:111] op_sel:[0,1] op_sel_hi:[1,0]
	v_pk_mul_f32 v[110:111], v[26:27], v[66:67] op_sel_hi:[1,0]
	v_pk_mul_f32 v[146:147], v[122:123], v[122:123]
	v_pk_fma_f32 v[110:111], v[110:111], v[70:71], v[158:159] op_sel_hi:[1,0,1] neg_lo:[1,0,0] neg_hi:[1,0,0]
	v_mul_f32_e32 v142, v119, v119
	v_mul_f32_e32 v140, v111, v111
	v_pk_fma_f32 v[112:113], v[144:145], v[70:71], v[112:113] op_sel_hi:[1,0,1] neg_lo:[1,0,0] neg_hi:[1,0,0]
	v_mov_b32_e32 v137, v146
	v_mov_b32_e32 v139, v147
	v_pk_fma_f32 v[140:141], v[110:111], v[110:111], v[140:141] op_sel_hi:[1,1,0]
	v_pk_fma_f32 v[142:143], v[118:119], v[118:119], v[142:143] op_sel_hi:[1,1,0]
	v_pk_mul_f32 v[144:145], v[112:113], v[112:113]
	v_pk_add_f32 v[136:137], v[136:137], v[138:139]
	v_pk_mul_f32 v[138:139], v[2:3], v[66:67] op_sel_hi:[1,0]
	v_mov_b32_e32 v143, v144
	v_mov_b32_e32 v141, v145
	v_pk_fma_f32 v[124:125], v[138:139], v[70:71], v[124:125] op_sel_hi:[1,0,1] neg_lo:[1,0,0] neg_hi:[1,0,0]
	v_pk_mul_f32 v[138:139], v[0:1], v[66:67] op_sel_hi:[1,0]
	v_pk_add_f32 v[140:141], v[142:143], v[140:141]
	v_pk_fma_f32 v[132:133], v[138:139], v[70:71], v[132:133] op_sel_hi:[1,0,1] neg_lo:[1,0,0] neg_hi:[1,0,0]
	v_pk_mul_f32 v[144:145], v[10:11], v[66:67] op_sel_hi:[1,0]
	v_pk_mul_f32 v[146:147], v[8:9], v[66:67] op_sel_hi:[1,0]
	v_pk_add_f32 v[136:137], v[136:137], v[140:141]
	v_mov_b32_e32 v140, v133
	v_mov_b32_e32 v141, v125
	v_pk_fma_f32 v[130:131], v[144:145], v[70:71], v[130:131] op_sel_hi:[1,0,1] neg_lo:[1,0,0] neg_hi:[1,0,0]
	v_pk_fma_f32 v[120:121], v[146:147], v[70:71], v[120:121] op_sel_hi:[1,0,1] neg_lo:[1,0,0] neg_hi:[1,0,0]
	v_mov_b32_e32 v138, v132
	v_mov_b32_e32 v139, v124
	v_pk_mul_f32 v[140:141], v[140:141], v[140:141]
	v_mul_f32_e32 v144, v131, v131
	v_mul_f32_e32 v146, v121, v121
	v_pk_mul_f32 v[128:129], v[68:69], v[68:69]
	v_pk_fma_f32 v[138:139], v[138:139], v[138:139], v[140:141]
	v_pk_mul_f32 v[140:141], v[6:7], v[66:67] op_sel_hi:[1,0]
	v_pk_mul_f32 v[142:143], v[4:5], v[66:67] op_sel_hi:[1,0]
	v_pk_fma_f32 v[144:145], v[130:131], v[130:131], v[144:145] op_sel_hi:[1,1,0]
	v_pk_fma_f32 v[146:147], v[120:121], v[120:121], v[146:147] op_sel_hi:[1,1,0]
	v_pk_fma_f32 v[126:127], v[140:141], v[70:71], v[126:127] op_sel_hi:[1,0,1] neg_lo:[1,0,0] neg_hi:[1,0,0]
	v_pk_fma_f32 v[134:135], v[142:143], v[70:71], v[134:135] op_sel_hi:[1,0,1] neg_lo:[1,0,0] neg_hi:[1,0,0]
	v_mov_b32_e32 v147, v128
	v_mov_b32_e32 v145, v129
	v_mul_f32_e32 v140, v127, v127
	v_mul_f32_e32 v142, v135, v135
	v_pk_add_f32 v[128:129], v[146:147], v[144:145]
	v_pk_mul_f32 v[144:145], v[12:13], v[66:67] op_sel_hi:[1,0]
	v_pk_add_f32 v[136:137], v[136:137], v[136:137] op_sel:[0,1] op_sel_hi:[1,0]
	v_pk_add_f32 v[138:139], v[138:139], v[138:139] op_sel:[0,1] op_sel_hi:[1,0]
; __device__ __forceinline__ unsigned cvtpk(float lo, float hi) { f32x2_t v = {lo, hi}; bf16x2_t b = __builtin_convertvector(v, bf16x2_t); return __builtin_bit_cast(unsigned, b); }
; __device__ __forceinline__ float xhalf_sum(float m) { unsigned a = __builtin_bit_cast(unsigned, m), b = a; xswap(a, b); return __builtin_bit_cast(float, a) + __builtin_bit_cast(float, b); }
; __device__ __forceinline__ void attn_unit_a(FLAS unsigned char* lds, const Unit u) {
;     ...
;                 o[db][4 * g] = x0; o[db][4 * g + 1] = x1; o[db][4 * g + 2] = x2; o[db][4 * g + 3] = x3; ss += (x0 * x0 + x1 * x1) + (x2 * x2 + x3 * x3); }
;         const float rr = 1.0f / sqrtf(xhalf_sum(ss) * (1.f / 128.f) + 1e-6f) * gsc;
; #pragma unroll
;         for (int db = 0; db < NDB; ++db)
; #pragma unroll
;             for (int g = 0; g < 4; ++g) { const float* gp = u.sgain + db * 32 + 8 * g + 4 * hi; u32x2 w;
;                 w.x = cvtpk(o[db][4 * g] * rr * gp[0], o[db][4 * g + 1] * rr * gp[1]); w.y = cvtpk(o[db][4 * g + 2] * rr * gp[2], o[db][4 * g + 3] * rr * gp[3]);
;                 *(u32x2*)(op + db * 32 + 8 * g) = w; }
	v_pk_fma_f32 v[140:141], v[126:127], v[126:127], v[140:141] op_sel_hi:[1,1,0]
	v_pk_fma_f32 v[142:143], v[134:135], v[134:135], v[142:143] op_sel_hi:[1,1,0]
	v_pk_fma_f32 v[70:71], v[144:145], v[70:71], v[114:115] op_sel_hi:[1,0,1] neg_lo:[1,0,0] neg_hi:[1,0,0]
	v_pk_add_f32 v[114:115], v[136:137], v[138:139]
	v_pk_mul_f32 v[136:137], v[70:71], v[70:71]
	v_pk_add_f32 v[138:139], v[142:143], v[140:141]
	v_mov_b32_e32 v115, v136
	v_mov_b32_e32 v139, v137
	v_pk_add_f32 v[114:115], v[114:115], v[138:139]
	s_nop 0
	v_pk_add_f32 v[114:115], v[114:115], v[128:129]
	s_nop 0
	v_pk_add_f32 v[114:115], v[114:115], v[114:115] op_sel:[0,1] op_sel_hi:[1,0]
	s_nop 0
	v_mov_b32_e32 v115, v114
	s_nop 1
	v_permlane32_swap_b32 v115, v114
	s_nop 1
	global_load_dwordx4 v[160:163], v67, s[8:9]
	global_load_dwordx4 v[164:167], v67, s[8:9] offset:32
	global_load_dwordx4 v[168:171], v67, s[8:9] offset:64
	global_load_dwordx4 v[172:175], v67, s[8:9] offset:96
	global_load_dwordx4 v[176:179], v67, s[8:9] offset:128
	global_load_dwordx4 v[180:183], v67, s[8:9] offset:160
	global_load_dwordx4 v[184:187], v67, s[8:9] offset:192
	global_load_dwordx4 v[200:203], v67, s[8:9] offset:224
	v_add_f32_e32 v114, v115, v114
	v_fmamk_f32 v114, v114, 0x3c000000, v240
	v_mul_f32_e32 v115, 0x4f800000, v114
	v_cmp_gt_f32_e32 vcc, s35, v114
	s_nop 1
	v_cndmask_b32_e32 v114, v114, v115, vcc
	v_sqrt_f32_e32 v115, v114
	s_nop 0
	v_add_u32_e32 v128, -1, v115
	v_fma_f32 v129, -v128, v115, v114
	v_cmp_ge_f32_e64 s[4:5], 0, v129
	v_add_u32_e32 v129, 1, v115
	s_nop 0
	v_cndmask_b32_e64 v128, v115, v128, s[4:5]
	v_fma_f32 v115, -v129, v115, v114
	v_cmp_lt_f32_e64 s[4:5], 0, v115
	s_nop 1
	v_cndmask_b32_e64 v115, v128, v129, s[4:5]
	v_mul_f32_e32 v128, 0x37800000, v115
	v_cndmask_b32_e32 v115, v115, v128, vcc
	v_cmp_class_f32_e32 vcc, v114, v244
	s_mov_b64 s[4:5], 0
	s_nop 0
	v_cndmask_b32_e32 v114, v115, v114, vcc
	v_div_scale_f32 v115, s[0:1], v114, v114, 1.0
	v_rcp_f32_e32 v128, v115
	s_nop 0
	v_fma_f32 v129, -v115, v128, 1.0
	v_fmac_f32_e32 v128, v129, v128
	v_div_scale_f32 v129, vcc, 1.0, v114, 1.0
	v_mul_f32_e32 v140, v129, v128
	v_fma_f32 v141, -v115, v140, v129
	v_fmac_f32_e32 v140, v141, v128
	v_fma_f32 v115, -v115, v140, v129
	v_div_fmas_f32 v115, v115, v128, v140
	v_div_fixup_f32 v114, v115, v114, 1.0
	v_mul_f32_e32 v114, v237, v114
	v_pk_mul_f32 v[78:79], v[78:79], v[114:115] op_sel_hi:[1,0]
	v_pk_mul_f32 v[72:73], v[72:73], v[114:115] op_sel_hi:[1,0]
	v_pk_mul_f32 v[74:75], v[74:75], v[114:115] op_sel_hi:[1,0]
	v_pk_mul_f32 v[76:77], v[76:77], v[114:115] op_sel_hi:[1,0]
	v_pk_mul_f32 v[70:71], v[70:71], v[114:115] op_sel_hi:[1,0]
	v_pk_mul_f32 v[68:69], v[68:69], v[114:115] op_sel_hi:[1,0]
	s_waitcnt vmcnt(7)
	v_pk_mul_f32 v[78:79], v[160:161], v[78:79]
	v_pk_mul_f32 v[72:73], v[162:163], v[72:73]
	v_cvt_pk_bf16_f32 v78, v78, v79
	v_cvt_pk_bf16_f32 v79, v72, v73
	global_store_dwordx2 v[64:65], v[78:79], off
	global_load_dwordx4 v[160:163], v67, s[8:9] offset:256
	v_pk_mul_f32 v[72:73], v[80:81], v[114:115] op_sel_hi:[1,0]
	v_pk_mul_f32 v[78:79], v[82:83], v[114:115] op_sel_hi:[1,0]
	s_waitcnt vmcnt(8)
	v_pk_mul_f32 v[72:73], v[164:165], v[72:73]
	v_pk_mul_f32 v[74:75], v[166:167], v[74:75]
	v_cvt_pk_bf16_f32 v72, v72, v73
	v_cvt_pk_bf16_f32 v73, v74, v75
	global_store_dwordx2 v[64:65], v[72:73], off offset:16
	global_load_dwordx4 v[164:167], v67, s[8:9] offset:288
	s_waitcnt vmcnt(9)
	v_pk_mul_f32 v[72:73], v[78:79], v[168:169]
	v_pk_mul_f32 v[74:75], v[76:77], v[170:171]
	v_cvt_pk_bf16_f32 v72, v72, v73
	v_cvt_pk_bf16_f32 v73, v74, v75
	global_store_dwordx2 v[64:65], v[72:73], off offset:32
	global_load_dwordx4 v[168:171], v67, s[8:9] offset:320
	v_pk_mul_f32 v[76:77], v[90:91], v[114:115] op_sel_hi:[1,0]
	v_pk_mul_f32 v[78:79], v[84:85], v[114:115] op_sel_hi:[1,0]
	s_waitcnt vmcnt(10)
	v_pk_mul_f32 v[72:73], v[76:77], v[172:173]
	v_pk_mul_f32 v[74:75], v[78:79], v[174:175]
	v_cvt_pk_bf16_f32 v72, v72, v73
	v_cvt_pk_bf16_f32 v73, v74, v75
	global_store_dwordx2 v[64:65], v[72:73], off offset:48
	global_load_dwordx4 v[172:175], v67, s[8:9] offset:352
	v_pk_mul_f32 v[76:77], v[92:93], v[114:115] op_sel_hi:[1,0]
	v_pk_mul_f32 v[78:79], v[86:87], v[114:115] op_sel_hi:[1,0]
	s_waitcnt vmcnt(11)
; __device__ __forceinline__ unsigned cvtpk(float lo, float hi) { f32x2_t v = {lo, hi}; bf16x2_t b = __builtin_convertvector(v, bf16x2_t); return __builtin_bit_cast(unsigned, b); }
; __device__ __forceinline__ void attn_unit_a(FLAS unsigned char* lds, const Unit u) {
;     ...
; #pragma unroll
;         for (int db = 0; db < NDB; ++db)
; #pragma unroll
;             for (int g = 0; g < 4; ++g) { const float* gp = u.sgain + db * 32 + 8 * g + 4 * hi; u32x2 w;
;                 w.x = cvtpk(o[db][4 * g] * rr * gp[0], o[db][4 * g + 1] * rr * gp[1]); w.y = cvtpk(o[db][4 * g + 2] * rr * gp[2], o[db][4 * g + 3] * rr * gp[3]);
;                 *(u32x2*)(op + db * 32 + 8 * g) = w; }
	v_pk_mul_f32 v[72:73], v[76:77], v[176:177]
	v_pk_mul_f32 v[74:75], v[78:79], v[178:179]
	v_cvt_pk_bf16_f32 v72, v72, v73
	v_cvt_pk_bf16_f32 v73, v74, v75
	global_store_dwordx2 v[64:65], v[72:73], off offset:64
	global_load_dwordx4 v[176:179], v67, s[8:9] offset:384
	v_pk_mul_f32 v[76:77], v[94:95], v[114:115] op_sel_hi:[1,0]
	v_pk_mul_f32 v[78:79], v[88:89], v[114:115] op_sel_hi:[1,0]
	s_waitcnt vmcnt(12)
	v_pk_mul_f32 v[72:73], v[76:77], v[180:181]
	v_pk_mul_f32 v[74:75], v[78:79], v[182:183]
	v_cvt_pk_bf16_f32 v72, v72, v73
	v_cvt_pk_bf16_f32 v73, v74, v75
	global_store_dwordx2 v[64:65], v[72:73], off offset:80
	global_load_dwordx4 v[180:183], v67, s[8:9] offset:416
	v_pk_mul_f32 v[76:77], v[102:103], v[114:115] op_sel_hi:[1,0]
	v_pk_mul_f32 v[78:79], v[96:97], v[114:115] op_sel_hi:[1,0]
	s_waitcnt vmcnt(13)
	v_pk_mul_f32 v[72:73], v[76:77], v[184:185]
	v_pk_mul_f32 v[74:75], v[78:79], v[186:187]
	v_cvt_pk_bf16_f32 v72, v72, v73
	v_cvt_pk_bf16_f32 v73, v74, v75
	global_store_dwordx2 v[64:65], v[72:73], off offset:96
	global_load_dwordx4 v[184:187], v67, s[8:9] offset:448
	v_pk_mul_f32 v[76:77], v[106:107], v[114:115] op_sel_hi:[1,0]
	v_pk_mul_f32 v[78:79], v[98:99], v[114:115] op_sel_hi:[1,0]
	s_waitcnt vmcnt(14)
	v_pk_mul_f32 v[72:73], v[76:77], v[200:201]
	v_pk_mul_f32 v[74:75], v[78:79], v[202:203]
	v_cvt_pk_bf16_f32 v72, v72, v73
	v_cvt_pk_bf16_f32 v73, v74, v75
	global_store_dwordx2 v[64:65], v[72:73], off offset:112
	global_load_dwordx4 v[200:203], v67, s[8:9] offset:480
	v_pk_mul_f32 v[76:77], v[104:105], v[114:115] op_sel_hi:[1,0]
	v_pk_mul_f32 v[78:79], v[100:101], v[114:115] op_sel_hi:[1,0]
	s_waitcnt vmcnt(14)
	v_pk_mul_f32 v[72:73], v[76:77], v[160:161]
	v_pk_mul_f32 v[74:75], v[78:79], v[162:163]
	v_cvt_pk_bf16_f32 v72, v72, v73
	v_cvt_pk_bf16_f32 v73, v74, v75
	global_store_dwordx2 v[64:65], v[72:73], off offset:128
	v_pk_mul_f32 v[76:77], v[116:117], v[114:115] op_sel_hi:[1,0]
	v_pk_mul_f32 v[78:79], v[108:109], v[114:115] op_sel_hi:[1,0]
	s_waitcnt vmcnt(13)
	v_pk_mul_f32 v[72:73], v[76:77], v[164:165]
	v_pk_mul_f32 v[74:75], v[78:79], v[166:167]
	v_cvt_pk_bf16_f32 v72, v72, v73
	v_cvt_pk_bf16_f32 v73, v74, v75
	global_store_dwordx2 v[64:65], v[72:73], off offset:144
	v_pk_mul_f32 v[76:77], v[118:119], v[114:115] op_sel_hi:[1,0]
	v_pk_mul_f32 v[78:79], v[110:111], v[114:115] op_sel_hi:[1,0]
	s_waitcnt vmcnt(12)
	v_pk_mul_f32 v[72:73], v[76:77], v[168:169]
	v_pk_mul_f32 v[74:75], v[78:79], v[170:171]
	v_cvt_pk_bf16_f32 v72, v72, v73
	v_cvt_pk_bf16_f32 v73, v74, v75
	global_store_dwordx2 v[64:65], v[72:73], off offset:160
	v_pk_mul_f32 v[76:77], v[122:123], v[114:115] op_sel_hi:[1,0]
	v_pk_mul_f32 v[78:79], v[112:113], v[114:115] op_sel_hi:[1,0]
	s_waitcnt vmcnt(11)
	v_pk_mul_f32 v[72:73], v[76:77], v[172:173]
	v_pk_mul_f32 v[74:75], v[78:79], v[174:175]
	v_cvt_pk_bf16_f32 v72, v72, v73
	v_cvt_pk_bf16_f32 v73, v74, v75
	global_store_dwordx2 v[64:65], v[72:73], off offset:176
	v_pk_mul_f32 v[76:77], v[132:133], v[114:115] op_sel_hi:[1,0]
	v_pk_mul_f32 v[78:79], v[124:125], v[114:115] op_sel_hi:[1,0]
	s_waitcnt vmcnt(10)
	v_pk_mul_f32 v[72:73], v[76:77], v[176:177]
	v_pk_mul_f32 v[74:75], v[78:79], v[178:179]
	v_cvt_pk_bf16_f32 v72, v72, v73
	v_cvt_pk_bf16_f32 v73, v74, v75
	global_store_dwordx2 v[64:65], v[72:73], off offset:192
	v_pk_mul_f32 v[76:77], v[134:135], v[114:115] op_sel_hi:[1,0]
	v_pk_mul_f32 v[78:79], v[126:127], v[114:115] op_sel_hi:[1,0]
	s_waitcnt vmcnt(9)
	v_pk_mul_f32 v[72:73], v[76:77], v[180:181]
	v_pk_mul_f32 v[74:75], v[78:79], v[182:183]
	v_cvt_pk_bf16_f32 v72, v72, v73
	v_cvt_pk_bf16_f32 v73, v74, v75
	global_store_dwordx2 v[64:65], v[72:73], off offset:208
	v_pk_mul_f32 v[76:77], v[120:121], v[114:115] op_sel_hi:[1,0]
	v_pk_mul_f32 v[78:79], v[130:131], v[114:115] op_sel_hi:[1,0]
	s_waitcnt vmcnt(8)
	v_pk_mul_f32 v[72:73], v[76:77], v[184:185]
	v_pk_mul_f32 v[74:75], v[78:79], v[186:187]
	v_cvt_pk_bf16_f32 v72, v72, v73
	v_cvt_pk_bf16_f32 v73, v74, v75
	global_store_dwordx2 v[64:65], v[72:73], off offset:224
	s_waitcnt vmcnt(7)
	v_pk_mul_f32 v[72:73], v[70:71], v[200:201]
	v_pk_mul_f32 v[70:71], v[68:69], v[202:203]
	v_cvt_pk_bf16_f32 v68, v72, v73
